# s_setprio 2 around the QK and PV MFMA clusters of the three flash loops
# speedup vs baseline: 1.2392x; 1.0195x over previous
; __device__ __forceinline__ f32x4 mfma16(bf16x8 a, bf16x8 b, f32x4 c) { return __builtin_amdgcn_mfma_f32_16x16x32_bf16(a, b, c, 0, 0, 0); }
; template <int KW, int VD, bool SEL> ...
;     ...
;         const float mref0 = (mrow[0] < -1e29f) ? 0.f : mrow[0], mref1 = (mrow[1] < -1e29f) ? 0.f : mrow[1];
;         const float ci0 = (SEL && !((((const u64*)(smem + 69632))[fr] >> j) & 1ull)) ? -1e30f : -mref0;
;         const float ci1 = (SEL && !((((const u64*)(smem + 69632))[16 + fr] >> j) & 1ull)) ? -1e30f : -mref1;
;         const f32x4 cinit0 = (f32x4){ci0, ci0, ci0, ci0}, cinit1 = (f32x4){ci1, ci1, ci1, ci1};
; #pragma unroll
;         for (int tt = 0; tt < 4; ++tt) {
;             const int kr = 32 * (tt >> 1) + (fr >> 2) * 8 + (tt & 1) * 4 + (fr & 3);
;             const bf16x8 kf0 = *(const bf16x8*)(sK + kr * KROWB + (((kcol >> 3) + fq) ^ kswz) * 16);
;             const bf16x8 kf1 = *(const bf16x8*)(sK + kr * KROWB + (((kcol >> 3) + 4 + fq) ^ kswz) * 16);
;             s[0][tt] = mfma16(kf0, qf[0][0], cinit0);
;             s[1][tt] = mfma16(kf0, qf[1][0], cinit1);
;             s[0][tt] = mfma16(kf1, qf[0][1], s[0][tt]);
;             s[1][tt] = mfma16(kf1, qf[1][1], s[1][tt]);
;         }
;         const bool pm = (j * 64 + 63 > tmin) || (j * 64 <= lomax);
.Lfh_sel_nodma:
	s_lshl_b64 s[0:1], 1, s4
	v_cmp_ngt_f32_e32 vcc, s16, v130
	s_waitcnt lgkmcnt(0)
	v_and_b32_e32 v107, s1, v53
	v_and_b32_e32 v106, s0, v52
	v_and_b32_e32 v3, s1, v55
	v_and_b32_e32 v2, s0, v54
	ds_read_b128 v[52:55], v141 offset:512
	v_cndmask_b32_e32 v171, 0, v130, vcc
	v_cmp_ngt_f32_e32 vcc, s16, v0
	v_add_u32_e32 v166, v72, v126
	ds_read_b128 v[72:75], v166
	ds_read_b128 v[76:79], v166 offset:512
	v_cndmask_b32_e32 v131, 0, v0, vcc
	v_cmp_ne_u64_e32 vcc, 0, v[106:107]
	s_lshl_b32 s13, s4, 6
	s_or_b32 s0, s13, 63
	v_cndmask_b32_e64 v64, v85, -v171, vcc
	v_mov_b32_e32 v65, v64
	v_mov_b32_e32 v66, v64
	v_mov_b32_e32 v67, v64
	v_cmp_ne_u64_e32 vcc, 0, v[2:3]
	s_cmp_le_u32 s0, s21
	s_setprio 2
	v_mfma_f32_16x16x32_bf16 v[60:63], v[56:59], v[4:7], v[64:67]
	v_cndmask_b32_e64 v68, v85, -v131, vcc
	v_mov_b32_e32 v69, v68
	v_mov_b32_e32 v70, v68
	v_mov_b32_e32 v71, v68
	s_waitcnt lgkmcnt(1)
	v_mfma_f32_16x16x32_bf16 v[80:83], v[72:75], v[8:11], v[60:63]
	s_cselect_b64 s[4:5], -1, 0
	s_cmp_gt_u32 s0, s21
	s_mov_b64 s[0:1], -1
	v_mfma_f32_16x16x32_bf16 v[56:59], v[56:59], v[12:15], v[68:71]
	v_mfma_f32_16x16x32_bf16 v[60:63], v[52:55], v[4:7], v[64:67]
	v_mfma_f32_16x16x32_bf16 v[52:55], v[52:55], v[12:15], v[68:71]
	v_mfma_f32_16x16x32_bf16 v[56:59], v[72:75], v[16:19], v[56:59]
	s_waitcnt lgkmcnt(0)
	v_mfma_f32_16x16x32_bf16 v[72:75], v[76:79], v[8:11], v[60:63]
	v_mfma_f32_16x16x32_bf16 v[60:63], v[76:79], v[16:19], v[52:55]
	s_nop 3
	ds_read_b128 v[52:55], v141 offset:4096
	ds_read_b128 v[142:145], v141 offset:4608
	ds_read_b128 v[162:165], v166 offset:4096
	ds_read_b128 v[166:169], v166 offset:4608
	s_waitcnt lgkmcnt(3)
	v_mfma_f32_16x16x32_bf16 v[76:79], v[52:55], v[4:7], v[64:67]
	v_mfma_f32_16x16x32_bf16 v[52:55], v[52:55], v[12:15], v[68:71]
	s_waitcnt lgkmcnt(2)
	v_mfma_f32_16x16x32_bf16 v[64:67], v[142:145], v[4:7], v[64:67]
	v_mfma_f32_16x16x32_bf16 v[142:145], v[142:145], v[12:15], v[68:71]
	s_waitcnt lgkmcnt(1)
	v_mfma_f32_16x16x32_bf16 v[76:79], v[162:165], v[8:11], v[76:79]
	v_mfma_f32_16x16x32_bf16 v[52:55], v[162:165], v[16:19], v[52:55]
	s_waitcnt lgkmcnt(0)
	v_mfma_f32_16x16x32_bf16 v[68:71], v[166:169], v[8:11], v[64:67]
	v_mfma_f32_16x16x32_bf16 v[64:67], v[166:169], v[16:19], v[142:145]
	s_setprio 0
	s_cbranch_scc1 .LBB0_375
	s_mov_b64 s[0:1], 0

; __device__ __forceinline__ unsigned cvt_pk_bf16(float lo, float hi) { const f32x2_t f = {lo, hi}; return __builtin_bit_cast(unsigned, __builtin_convertvector(f, bf16x2_t)); }
; __device__ __forceinline__ f32x4 mfma16(bf16x8 a, bf16x8 b, f32x4 c) { return __builtin_amdgcn_mfma_f32_16x16x32_bf16(a, b, c, 0, 0, 0); }
; template <int KW, int VD, bool SEL> ...
;     ...
;             float ps = 0.f;
; #pragma unroll
;             for (int tt = 0; tt < 4; ++tt)
; #pragma unroll
;                 for (int jj = 0; jj < 4; ++jj) { s[qt][tt][jj] = __builtin_amdgcn_exp2f(s[qt][tt][jj]); ps += s[qt][tt][jj]; }
;             lrow[qt] += ps;
; #pragma unroll
;             for (int i = 0; i < 2; ++i) {
;                 u32x4 pk;
;                 pk.x = cvt_pk_bf16(s[qt][2 * i][0], s[qt][2 * i][1]); pk.y = cvt_pk_bf16(s[qt][2 * i][2], s[qt][2 * i][3]);
;                 pk.z = cvt_pk_bf16(s[qt][2 * i + 1][0], s[qt][2 * i + 1][1]); pk.w = cvt_pk_bf16(s[qt][2 * i + 1][2], s[qt][2 * i + 1][3]);
;                 pf[qt][i] = __builtin_bit_cast(bf16x8, pk);
;             }
;         }
; #pragma unroll
;         for (int i = 0; i < 2; ++i) {
; #pragma unroll
;             for (int dt = 0; dt < VD / 16; ++dt) {
;                 const bf16x8 vf = *(const bf16x8*)(sV + (dt * 16 + fr) * 128 + ((i * 4 + fq) ^ vswz) * 16);
;                 O[0][dt] = mfma16(vf, pf[0][i], O[0][dt]);
;                 O[1][dt] = mfma16(vf, pf[1][i], O[1][dt]);
;             }
;         }
;         asm volatile("s_waitcnt vmcnt(0)" ::: "memory");
;         __syncthreads();
;         if (jn < 0) break;
;         j = jn; cur ^= 1;
;     }
;     ...
; #pragma unroll
;     for (int qt = 0; qt < 2; ++qt) { lrow[qt] += __shfl_xor(lrow[qt], 16); lrow[qt] += __shfl_xor(lrow[qt], 32); }
.LBB0_385:
	v_exp_f32_e32 v2, v80
	v_exp_f32_e32 v3, v81
	v_exp_f32_e32 v80, v82
	v_exp_f32_e32 v81, v83
	v_add_f32_e32 v82, 0, v2
	v_exp_f32_e32 v72, v72
	v_add_f32_e32 v82, v3, v82
	v_exp_f32_e32 v73, v73
	v_add_f32_e32 v82, v80, v82
	v_exp_f32_e32 v74, v74
	v_add_f32_e32 v82, v81, v82
	v_exp_f32_e32 v75, v75
	v_add_f32_e32 v82, v72, v82
	v_exp_f32_e32 v76, v76
	v_add_f32_e32 v82, v73, v82
	v_exp_f32_e32 v77, v77
	v_add_f32_e32 v82, v74, v82
	v_exp_f32_e32 v78, v78
	v_add_f32_e32 v82, v75, v82
	v_exp_f32_e32 v79, v79
	v_add_f32_e32 v82, v76, v82
	v_exp_f32_e32 v83, v68
	v_exp_f32_e32 v106, v69
	v_cvt_pk_bf16_f32 v69, v80, v81
	v_add_u32_e32 v80, s12, v128
	v_add_f32_e32 v82, v77, v82
	v_add_u32_e32 v81, v80, v125
	v_add_f32_e32 v82, v78, v82
	v_exp_f32_e32 v107, v70
	v_exp_f32_e32 v131, v71
	v_cvt_pk_bf16_f32 v70, v72, v73
	v_cvt_pk_bf16_f32 v71, v74, v75
	ds_read_b128 v[72:75], v81 offset:8192
	v_add_f32_e32 v68, v79, v82
	v_add_f32_e32 v68, v83, v68
	v_exp_f32_e32 v143, v60
	v_exp_f32_e32 v144, v61
	v_exp_f32_e32 v145, v62
	v_exp_f32_e32 v162, v63
	ds_read_b128 v[60:63], v81 offset:10240
	v_add_f32_e32 v68, v106, v68
	v_add_f32_e32 v82, v107, v68
	v_cvt_pk_bf16_f32 v68, v2, v3
	v_exp_f32_e32 v2, v56
	v_exp_f32_e32 v3, v57
	v_exp_f32_e32 v141, v58
	v_exp_f32_e32 v142, v59
	v_cvt_pk_bf16_f32 v58, v143, v144
	v_cvt_pk_bf16_f32 v56, v2, v3
	v_cvt_pk_bf16_f32 v59, v145, v162
	v_cvt_pk_bf16_f32 v57, v141, v142
	s_waitcnt lgkmcnt(1)
	s_setprio 2
	v_mfma_f32_16x16x32_bf16 v[48:51], v[72:75], v[68:71], v[48:51]
	v_cvt_pk_bf16_f32 v76, v76, v77
	v_cvt_pk_bf16_f32 v77, v78, v79
	v_cvt_pk_bf16_f32 v78, v83, v106
	v_mfma_f32_16x16x32_bf16 v[32:35], v[72:75], v[56:59], v[32:35]
	v_add_f32_e32 v72, v131, v82
	v_add_f32_e32 v105, v105, v72
	ds_read_b128 v[72:75], v81 offset:12288
	s_waitcnt lgkmcnt(1)
	v_mfma_f32_16x16x32_bf16 v[44:47], v[60:63], v[68:71], v[44:47]
	v_exp_f32_e32 v82, v53
	v_exp_f32_e32 v83, v54
	v_exp_f32_e32 v64, v64
	v_mfma_f32_16x16x32_bf16 v[28:31], v[60:63], v[56:59], v[28:31]
	ds_read_b128 v[60:63], v81 offset:14336
	v_exp_f32_e32 v81, v52
	v_exp_f32_e32 v65, v65
	s_waitcnt lgkmcnt(1)
	v_mfma_f32_16x16x32_bf16 v[40:43], v[72:75], v[68:71], v[40:43]
	v_exp_f32_e32 v66, v66
	v_exp_f32_e32 v67, v67
	v_add_f32_e32 v2, 0, v2
	v_mfma_f32_16x16x32_bf16 v[24:27], v[72:75], v[56:59], v[24:27]
	v_add_u32_e32 v73, v80, v126
	v_exp_f32_e32 v72, v55
	ds_read_b128 v[52:55], v73 offset:8192
	s_waitcnt lgkmcnt(1)
	v_mfma_f32_16x16x32_bf16 v[36:39], v[60:63], v[68:71], v[36:39]
	v_add_f32_e32 v2, v3, v2
	v_add_f32_e32 v2, v141, v2
	v_cvt_pk_bf16_f32 v79, v107, v131
	v_mfma_f32_16x16x32_bf16 v[20:23], v[60:63], v[56:59], v[20:23]
	ds_read_b128 v[60:63], v73 offset:10240
	v_cvt_pk_bf16_f32 v56, v81, v82
	v_cvt_pk_bf16_f32 v57, v83, v72
	v_cvt_pk_bf16_f32 v58, v64, v65
	v_cvt_pk_bf16_f32 v59, v66, v67
	v_add_f32_e32 v2, v142, v2
	s_waitcnt lgkmcnt(1)
	v_mfma_f32_16x16x32_bf16 v[48:51], v[52:55], v[76:79], v[48:51]
	v_add_f32_e32 v2, v143, v2
	v_add_f32_e32 v2, v144, v2
	v_add_f32_e32 v2, v145, v2
	v_mfma_f32_16x16x32_bf16 v[32:35], v[52:55], v[56:59], v[32:35]
	ds_read_b128 v[52:55], v73 offset:12288
	v_add_f32_e32 v2, v162, v2
	v_add_f32_e32 v2, v81, v2
	s_waitcnt lgkmcnt(1)
	v_mfma_f32_16x16x32_bf16 v[44:47], v[60:63], v[76:79], v[44:47]
	v_add_f32_e32 v2, v82, v2
	v_add_f32_e32 v2, v83, v2
	v_add_f32_e32 v2, v72, v2
	v_mfma_f32_16x16x32_bf16 v[28:31], v[60:63], v[56:59], v[28:31]
	ds_read_b128 v[60:63], v73 offset:14336
	v_add_f32_e32 v2, v64, v2
	v_add_f32_e32 v2, v65, v2
	s_waitcnt lgkmcnt(1)
	v_mfma_f32_16x16x32_bf16 v[40:43], v[52:55], v[76:79], v[40:43]
	v_add_f32_e32 v2, v66, v2
	s_waitcnt vmcnt(0)
	v_add_f32_e32 v2, v67, v2
	v_mfma_f32_16x16x32_bf16 v[24:27], v[52:55], v[56:59], v[24:27]
	s_xor_b32 s10, s10, 1
	v_add_f32_e32 v104, v104, v2
	s_cmp_gt_i32 s11, -1
	s_waitcnt lgkmcnt(0)
	v_mfma_f32_16x16x32_bf16 v[36:39], v[60:63], v[76:79], v[36:39]
	s_barrier
	v_mfma_f32_16x16x32_bf16 v[20:23], v[60:63], v[56:59], v[20:23]
	s_setprio 0
	s_cbranch_scc1 .LBB0_369
	ds_bpermute_b32 v3, v119, v105
	ds_bpermute_b32 v2, v119, v104
	s_waitcnt lgkmcnt(0)
	v_pk_add_f32 v[2:3], v[104:105], v[2:3]
	ds_bpermute_b32 v53, v118, v3
	ds_bpermute_b32 v52, v118, v2
	s_waitcnt lgkmcnt(0)
	v_pk_add_f32 v[2:3], v[2:3], v[52:53]
	s_branch .LBB0_388

; __device__ __forceinline__ f32x4 mfma16(bf16x8 a, bf16x8 b, f32x4 c) { return __builtin_amdgcn_mfma_f32_16x16x32_bf16(a, b, c, 0, 0, 0); }
; template <int KW, int VD, bool SEL> ...
;     ...
;         const float mref0 = (mrow[0] < -1e29f) ? 0.f : mrow[0], mref1 = (mrow[1] < -1e29f) ? 0.f : mrow[1];
;         const float ci0 = (SEL && !((((const u64*)(smem + 69632))[fr] >> j) & 1ull)) ? -1e30f : -mref0;
;         const float ci1 = (SEL && !((((const u64*)(smem + 69632))[16 + fr] >> j) & 1ull)) ? -1e30f : -mref1;
;         const f32x4 cinit0 = (f32x4){ci0, ci0, ci0, ci0}, cinit1 = (f32x4){ci1, ci1, ci1, ci1};
; #pragma unroll
;         for (int tt = 0; tt < 4; ++tt) {
;             const int kr = 32 * (tt >> 1) + (fr >> 2) * 8 + (tt & 1) * 4 + (fr & 3);
;             const bf16x8 kf0 = *(const bf16x8*)(sK + kr * KROWB + (((kcol >> 3) + fq) ^ kswz) * 16);
;             const bf16x8 kf1 = *(const bf16x8*)(sK + kr * KROWB + (((kcol >> 3) + 4 + fq) ^ kswz) * 16);
;             s[0][tt] = mfma16(kf0, qf[0][0], cinit0);
;             s[1][tt] = mfma16(kf0, qf[1][0], cinit1);
;             s[0][tt] = mfma16(kf1, qf[0][1], s[0][tt]);
;             s[1][tt] = mfma16(kf1, qf[1][1], s[1][tt]);
;         }
;         const bool pm = (j * 64 + 63 > tmin) || (j * 64 <= lomax);
.Lfh_win_nodma:
	v_cndmask_b32_e32 v167, 0, v0, vcc
	v_cmp_ngt_f32_e32 vcc, s16, v128
	v_xor_b32_e32 v64, 0x80000000, v167
	v_mov_b32_e32 v65, v64
	v_cndmask_b32_e32 v2, 0, v128, vcc
	v_xor_b32_e32 v76, 0x80000000, v2
	v_mov_b32_e32 v66, v64
	v_mov_b32_e32 v67, v64
	v_mov_b32_e32 v77, v76
	v_mov_b32_e32 v78, v76
	v_mov_b32_e32 v79, v76
	s_waitcnt lgkmcnt(0)
	s_setprio 2
	v_mfma_f32_16x16x32_bf16 v[56:59], v[52:55], v[4:7], v[64:67]
	s_lshl_b32 s14, s4, 6
	s_or_b32 s0, s14, 63
	s_cmp_gt_u32 s0, s21
	v_mfma_f32_16x16x32_bf16 v[52:55], v[52:55], v[12:15], v[76:79]
	s_cselect_b64 s[0:1], -1, 0
	s_cmp_le_i32 s14, s10
	s_cselect_b64 s[4:5], -1, 0
	v_mfma_f32_16x16x32_bf16 v[80:83], v[68:71], v[8:11], v[56:59]
	s_or_b64 s[4:5], s[4:5], s[0:1]
	s_mov_b64 s[0:1], -1
	s_and_b64 vcc, exec, s[4:5]
	v_mfma_f32_16x16x32_bf16 v[56:59], v[68:71], v[16:19], v[52:55]
	v_mfma_f32_16x16x32_bf16 v[52:55], v[60:63], v[4:7], v[64:67]
	v_mfma_f32_16x16x32_bf16 v[68:71], v[72:75], v[8:11], v[52:55]
	s_nop 6
	ds_read_b128 v[52:55], v129 offset:4096
	ds_read_b128 v[142:145], v129 offset:4608
	ds_read_b128 v[162:165], v3 offset:4096
	ds_read_b128 v[168:171], v3 offset:4608
	v_mfma_f32_16x16x32_bf16 v[60:63], v[60:63], v[12:15], v[76:79]
	v_mfma_f32_16x16x32_bf16 v[60:63], v[72:75], v[16:19], v[60:63]
	s_waitcnt lgkmcnt(3)
	v_mfma_f32_16x16x32_bf16 v[72:75], v[52:55], v[4:7], v[64:67]
	v_mfma_f32_16x16x32_bf16 v[52:55], v[52:55], v[12:15], v[76:79]
	s_waitcnt lgkmcnt(2)
	v_mfma_f32_16x16x32_bf16 v[64:67], v[142:145], v[4:7], v[64:67]
	v_mfma_f32_16x16x32_bf16 v[142:145], v[142:145], v[12:15], v[76:79]
	s_waitcnt lgkmcnt(1)
	v_mfma_f32_16x16x32_bf16 v[72:75], v[162:165], v[8:11], v[72:75]
	v_mfma_f32_16x16x32_bf16 v[52:55], v[162:165], v[16:19], v[52:55]
	s_waitcnt lgkmcnt(0)
	v_mfma_f32_16x16x32_bf16 v[76:79], v[168:171], v[8:11], v[64:67]
	v_mfma_f32_16x16x32_bf16 v[64:67], v[168:171], v[16:19], v[142:145]
	s_setprio 0
	s_cbranch_vccnz .LBB0_396
	s_mov_b64 s[0:1], 0

; __device__ __forceinline__ unsigned cvt_pk_bf16(float lo, float hi) { const f32x2_t f = {lo, hi}; return __builtin_bit_cast(unsigned, __builtin_convertvector(f, bf16x2_t)); }
; __device__ __forceinline__ f32x4 mfma16(bf16x8 a, bf16x8 b, f32x4 c) { return __builtin_amdgcn_mfma_f32_16x16x32_bf16(a, b, c, 0, 0, 0); }
; template <int KW, int VD, bool SEL> ...
;     ...
;             float ps = 0.f;
; #pragma unroll
;             for (int tt = 0; tt < 4; ++tt)
; #pragma unroll
;                 for (int jj = 0; jj < 4; ++jj) { s[qt][tt][jj] = __builtin_amdgcn_exp2f(s[qt][tt][jj]); ps += s[qt][tt][jj]; }
;             lrow[qt] += ps;
; #pragma unroll
;             for (int i = 0; i < 2; ++i) {
;                 u32x4 pk;
;                 pk.x = cvt_pk_bf16(s[qt][2 * i][0], s[qt][2 * i][1]); pk.y = cvt_pk_bf16(s[qt][2 * i][2], s[qt][2 * i][3]);
;                 pk.z = cvt_pk_bf16(s[qt][2 * i + 1][0], s[qt][2 * i + 1][1]); pk.w = cvt_pk_bf16(s[qt][2 * i + 1][2], s[qt][2 * i + 1][3]);
;                 pf[qt][i] = __builtin_bit_cast(bf16x8, pk);
;             }
;         }
; #pragma unroll
;         for (int i = 0; i < 2; ++i) {
; #pragma unroll
;             for (int dt = 0; dt < VD / 16; ++dt) {
;                 const bf16x8 vf = *(const bf16x8*)(sV + (dt * 16 + fr) * 128 + ((i * 4 + fq) ^ vswz) * 16);
;                 O[0][dt] = mfma16(vf, pf[0][i], O[0][dt]);
;                 O[1][dt] = mfma16(vf, pf[1][i], O[1][dt]);
;             }
;         }
;         asm volatile("s_waitcnt vmcnt(0)" ::: "memory");
;         __syncthreads();
;         if (jn < 0) break;
;         j = jn; cur ^= 1;
;     }
;     ...
; #pragma unroll
;     for (int qt = 0; qt < 2; ++qt) { lrow[qt] += __shfl_xor(lrow[qt], 16); lrow[qt] += __shfl_xor(lrow[qt], 32); }
.LBB0_406:
	v_exp_f32_e32 v2, v80
	v_exp_f32_e32 v3, v81
	v_exp_f32_e32 v80, v82
	v_exp_f32_e32 v81, v83
	v_add_f32_e32 v82, 0, v2
	v_exp_f32_e32 v83, v68
	v_add_f32_e32 v82, v3, v82
	v_exp_f32_e32 v129, v69
	v_add_f32_e32 v82, v80, v82
	v_exp_f32_e32 v130, v70
	v_add_f32_e32 v68, v81, v82
	v_exp_f32_e32 v71, v71
	v_add_f32_e32 v68, v83, v68
	v_exp_f32_e32 v82, v72
	v_add_f32_e32 v68, v129, v68
	v_exp_f32_e32 v131, v73
	v_add_f32_e32 v68, v130, v68
	v_exp_f32_e32 v141, v74
	v_add_f32_e32 v68, v71, v68
	v_exp_f32_e32 v142, v75
	v_add_f32_e32 v68, v82, v68
	v_exp_f32_e32 v143, v76
	v_cvt_pk_bf16_f32 v69, v80, v81
	v_add_u32_e32 v80, s13, v126
	v_add_f32_e32 v68, v131, v68
	v_exp_f32_e32 v144, v77
	v_add_u32_e32 v81, v80, v123
	v_add_f32_e32 v68, v141, v68
	v_exp_f32_e32 v145, v78
	ds_read_b128 v[72:75], v81 offset:8192
	v_add_f32_e32 v68, v142, v68
	v_add_f32_e32 v68, v143, v68
	v_cvt_pk_bf16_f32 v71, v130, v71
	v_exp_f32_e32 v130, v60
	v_exp_f32_e32 v162, v61
	v_exp_f32_e32 v163, v62
	v_exp_f32_e32 v164, v63
	ds_read_b128 v[60:63], v81 offset:10240
	v_add_f32_e32 v68, v144, v68
	v_add_f32_e32 v76, v145, v68
	v_cvt_pk_bf16_f32 v68, v2, v3
	v_cvt_pk_bf16_f32 v70, v83, v129
	v_exp_f32_e32 v2, v56
	v_exp_f32_e32 v3, v57
	v_exp_f32_e32 v83, v58
	v_exp_f32_e32 v129, v59
	v_exp_f32_e32 v79, v79
	v_cvt_pk_bf16_f32 v56, v2, v3
	v_cvt_pk_bf16_f32 v58, v130, v162
	v_cvt_pk_bf16_f32 v57, v83, v129
	v_cvt_pk_bf16_f32 v59, v163, v164
	s_waitcnt lgkmcnt(1)
	s_setprio 2
	v_mfma_f32_16x16x32_bf16 v[48:51], v[72:75], v[68:71], v[48:51]
	v_exp_f32_e32 v64, v64
	v_exp_f32_e32 v65, v65
	v_exp_f32_e32 v66, v66
	v_mfma_f32_16x16x32_bf16 v[32:35], v[72:75], v[56:59], v[32:35]
	v_add_f32_e32 v72, v79, v76
	v_add_f32_e32 v105, v105, v72
	ds_read_b128 v[72:75], v81 offset:12288
	s_waitcnt lgkmcnt(1)
	v_mfma_f32_16x16x32_bf16 v[44:47], v[60:63], v[68:71], v[44:47]
	v_cvt_pk_bf16_f32 v76, v82, v131
	v_exp_f32_e32 v82, v53
	v_exp_f32_e32 v131, v54
	v_mfma_f32_16x16x32_bf16 v[28:31], v[60:63], v[56:59], v[28:31]
	ds_read_b128 v[60:63], v81 offset:14336
	v_exp_f32_e32 v81, v52
	v_exp_f32_e32 v67, v67
	s_waitcnt lgkmcnt(1)
	v_mfma_f32_16x16x32_bf16 v[40:43], v[72:75], v[68:71], v[40:43]
	v_add_f32_e32 v2, 0, v2
	v_add_f32_e32 v2, v3, v2
	v_add_f32_e32 v2, v83, v2
	v_mfma_f32_16x16x32_bf16 v[24:27], v[72:75], v[56:59], v[24:27]
	v_add_u32_e32 v73, v80, v124
	v_exp_f32_e32 v72, v55
	ds_read_b128 v[52:55], v73 offset:8192
	s_waitcnt lgkmcnt(1)
	v_mfma_f32_16x16x32_bf16 v[36:39], v[60:63], v[68:71], v[36:39]
	v_cvt_pk_bf16_f32 v77, v141, v142
	v_cvt_pk_bf16_f32 v78, v143, v144
	v_cvt_pk_bf16_f32 v79, v145, v79
	v_mfma_f32_16x16x32_bf16 v[20:23], v[60:63], v[56:59], v[20:23]
	ds_read_b128 v[60:63], v73 offset:10240
	v_cvt_pk_bf16_f32 v56, v81, v82
	v_cvt_pk_bf16_f32 v57, v131, v72
	v_cvt_pk_bf16_f32 v58, v64, v65
	v_cvt_pk_bf16_f32 v59, v66, v67
	v_add_f32_e32 v2, v129, v2
	s_waitcnt lgkmcnt(1)
	v_mfma_f32_16x16x32_bf16 v[48:51], v[52:55], v[76:79], v[48:51]
	v_add_f32_e32 v2, v130, v2
	v_add_f32_e32 v2, v162, v2
	v_add_f32_e32 v2, v163, v2
	v_mfma_f32_16x16x32_bf16 v[32:35], v[52:55], v[56:59], v[32:35]
	ds_read_b128 v[52:55], v73 offset:12288
	v_add_f32_e32 v2, v164, v2
	v_add_f32_e32 v2, v81, v2
	s_waitcnt lgkmcnt(1)
	v_mfma_f32_16x16x32_bf16 v[44:47], v[60:63], v[76:79], v[44:47]
	v_add_f32_e32 v2, v82, v2
	v_add_f32_e32 v2, v131, v2
	v_add_f32_e32 v2, v72, v2
	v_mfma_f32_16x16x32_bf16 v[28:31], v[60:63], v[56:59], v[28:31]
	ds_read_b128 v[60:63], v73 offset:14336
	v_add_f32_e32 v2, v64, v2
	v_add_f32_e32 v2, v65, v2
	s_waitcnt lgkmcnt(1)
	v_mfma_f32_16x16x32_bf16 v[40:43], v[52:55], v[76:79], v[40:43]
	v_add_f32_e32 v2, v66, v2
	s_waitcnt vmcnt(0)
	v_add_f32_e32 v2, v67, v2
	v_mfma_f32_16x16x32_bf16 v[24:27], v[52:55], v[56:59], v[24:27]
	s_xor_b32 s11, s11, 1
	v_add_f32_e32 v104, v104, v2
	s_cmp_gt_i32 s12, -1
	s_waitcnt lgkmcnt(0)
	v_mfma_f32_16x16x32_bf16 v[36:39], v[60:63], v[76:79], v[36:39]
	s_barrier
	v_mfma_f32_16x16x32_bf16 v[20:23], v[60:63], v[56:59], v[20:23]
	s_setprio 0
	s_cbranch_scc1 .LBB0_390
	ds_bpermute_b32 v3, v119, v105
	ds_bpermute_b32 v2, v119, v104
	s_waitcnt lgkmcnt(0)
	v_pk_add_f32 v[2:3], v[104:105], v[2:3]
	ds_bpermute_b32 v5, v118, v3
	ds_bpermute_b32 v4, v118, v2
	s_waitcnt lgkmcnt(0)
	v_pk_add_f32 v[2:3], v[2:3], v[4:5]
	s_branch .LBB0_338

; __device__ __forceinline__ f32x4 mfma16(bf16x8 a, bf16x8 b, f32x4 c) { return __builtin_amdgcn_mfma_f32_16x16x32_bf16(a, b, c, 0, 0, 0); }
; template <int KW, int VD, bool SEL> ...
;     ...
;         const float mref0 = (mrow[0] < -1e29f) ? 0.f : mrow[0], mref1 = (mrow[1] < -1e29f) ? 0.f : mrow[1];
;         const float ci0 = (SEL && !((((const u64*)(smem + 69632))[fr] >> j) & 1ull)) ? -1e30f : -mref0;
;         const float ci1 = (SEL && !((((const u64*)(smem + 69632))[16 + fr] >> j) & 1ull)) ? -1e30f : -mref1;
;         const f32x4 cinit0 = (f32x4){ci0, ci0, ci0, ci0}, cinit1 = (f32x4){ci1, ci1, ci1, ci1};
; #pragma unroll
;         for (int tt = 0; tt < 4; ++tt) {
;             const int kr = 32 * (tt >> 1) + (fr >> 2) * 8 + (tt & 1) * 4 + (fr & 3);
;             const bf16x8 kf0 = *(const bf16x8*)(sK + kr * KROWB + (((kcol >> 3) + fq) ^ kswz) * 16);
;             const bf16x8 kf1 = *(const bf16x8*)(sK + kr * KROWB + (((kcol >> 3) + 4 + fq) ^ kswz) * 16);
;             s[0][tt] = mfma16(kf0, qf[0][0], cinit0);
;             s[1][tt] = mfma16(kf0, qf[1][0], cinit1);
;             s[0][tt] = mfma16(kf1, qf[0][1], s[0][tt]);
;             s[1][tt] = mfma16(kf1, qf[1][1], s[1][tt]);
;         }
;         const bool pm = (j * 64 + 63 > tmin) || (j * 64 <= lomax);
.Lfh_diff_nodma:
	v_cndmask_b32_e32 v199, 0, v182, vcc
	v_cmp_ngt_f32_e32 vcc, s13, v183
	v_xor_b32_e32 v84, 0x80000000, v199
	v_mov_b32_e32 v85, v84
	v_cndmask_b32_e32 v184, 0, v183, vcc
	v_xor_b32_e32 v88, 0x80000000, v184
	v_mov_b32_e32 v86, v84
	v_mov_b32_e32 v87, v84
	v_mov_b32_e32 v89, v88
	v_mov_b32_e32 v90, v88
	v_mov_b32_e32 v91, v88
	s_waitcnt lgkmcnt(0)
	s_setprio 2
	v_mfma_f32_16x16x32_bf16 v[96:99], v[80:83], v[64:67], v[84:87]
	s_lshl_b32 s27, s10, 6
	s_or_b32 s10, s27, 63
	s_cmp_le_u32 s10, s19
	v_mfma_f32_16x16x32_bf16 v[80:83], v[80:83], v[72:75], v[88:91]
	s_cselect_b64 s[8:9], -1, 0
	s_cmp_gt_u32 s10, s19
	s_mov_b64 s[10:11], -1
	v_mfma_f32_16x16x32_bf16 v[108:111], v[100:103], v[68:71], v[96:99]
	v_mfma_f32_16x16x32_bf16 v[96:99], v[100:103], v[76:79], v[80:83]
	v_mfma_f32_16x16x32_bf16 v[80:83], v[92:95], v[64:67], v[84:87]
	v_mfma_f32_16x16x32_bf16 v[92:95], v[92:95], v[72:75], v[88:91]
	v_mfma_f32_16x16x32_bf16 v[104:107], v[186:189], v[68:71], v[80:83]
	v_mfma_f32_16x16x32_bf16 v[100:103], v[186:189], v[76:79], v[92:95]
	s_nop 4
	ds_read_b128 v[80:83], v185 offset:8192
	ds_read_b128 v[186:189], v185 offset:9216
	ds_read_b128 v[190:193], v194 offset:8192
	ds_read_b128 v[194:197], v194 offset:9216
	s_waitcnt lgkmcnt(3)
	v_mfma_f32_16x16x32_bf16 v[92:95], v[80:83], v[64:67], v[84:87]
	v_mfma_f32_16x16x32_bf16 v[80:83], v[80:83], v[72:75], v[88:91]
	s_waitcnt lgkmcnt(2)
	v_mfma_f32_16x16x32_bf16 v[84:87], v[186:189], v[64:67], v[84:87]
	v_mfma_f32_16x16x32_bf16 v[186:189], v[186:189], v[72:75], v[88:91]
	s_waitcnt lgkmcnt(1)
	v_mfma_f32_16x16x32_bf16 v[92:95], v[190:193], v[68:71], v[92:95]
	v_mfma_f32_16x16x32_bf16 v[80:83], v[190:193], v[76:79], v[80:83]
	s_waitcnt lgkmcnt(0)
	v_mfma_f32_16x16x32_bf16 v[88:91], v[194:197], v[68:71], v[84:87]
	v_mfma_f32_16x16x32_bf16 v[84:87], v[194:197], v[76:79], v[186:189]
	s_setprio 0
	s_cbranch_scc1 .LBB0_826
	s_mov_b64 s[10:11], 0

; __device__ __forceinline__ unsigned cvt_pk_bf16(float lo, float hi) { const f32x2_t f = {lo, hi}; return __builtin_bit_cast(unsigned, __builtin_convertvector(f, bf16x2_t)); }
; __device__ __forceinline__ f32x4 mfma16(bf16x8 a, bf16x8 b, f32x4 c) { return __builtin_amdgcn_mfma_f32_16x16x32_bf16(a, b, c, 0, 0, 0); }
; template <int KW, int VD, bool SEL> ...
;     ...
;             float ps = 0.f;
; #pragma unroll
;             for (int tt = 0; tt < 4; ++tt)
; #pragma unroll
;                 for (int jj = 0; jj < 4; ++jj) { s[qt][tt][jj] = __builtin_amdgcn_exp2f(s[qt][tt][jj]); ps += s[qt][tt][jj]; }
;             lrow[qt] += ps;
; #pragma unroll
;             for (int i = 0; i < 2; ++i) {
;                 u32x4 pk;
;                 pk.x = cvt_pk_bf16(s[qt][2 * i][0], s[qt][2 * i][1]); pk.y = cvt_pk_bf16(s[qt][2 * i][2], s[qt][2 * i][3]);
;                 pk.z = cvt_pk_bf16(s[qt][2 * i + 1][0], s[qt][2 * i + 1][1]); pk.w = cvt_pk_bf16(s[qt][2 * i + 1][2], s[qt][2 * i + 1][3]);
;                 pf[qt][i] = __builtin_bit_cast(bf16x8, pk);
;             }
;         }
; #pragma unroll
;         for (int i = 0; i < 2; ++i) {
; #pragma unroll
;             for (int dt = 0; dt < VD / 16; ++dt) {
;                 const bf16x8 vf = *(const bf16x8*)(sV + (dt * 16 + fr) * 128 + ((i * 4 + fq) ^ vswz) * 16);
;                 O[0][dt] = mfma16(vf, pf[0][i], O[0][dt]);
;                 O[1][dt] = mfma16(vf, pf[1][i], O[1][dt]);
;             }
;         }
;         asm volatile("s_waitcnt vmcnt(0)" ::: "memory");
;         __syncthreads();
;         if (jn < 0) break;
;         j = jn; cur ^= 1;
;     }
;     ...
; #pragma unroll
;     for (int qt = 0; qt < 2; ++qt) { lrow[qt] += __shfl_xor(lrow[qt], 16); lrow[qt] += __shfl_xor(lrow[qt], 32); }
.LBB0_836:
	v_add_u32_e32 v194, s26, v178
	v_add_u32_e32 v195, v194, v180
	v_exp_f32_e32 v184, v108
	v_exp_f32_e32 v185, v109
	v_exp_f32_e32 v186, v110
	v_exp_f32_e32 v187, v111
	ds_read_b128 v[108:111], v195 offset:16384
	v_exp_f32_e32 v198, v100
	v_exp_f32_e32 v199, v101
	v_exp_f32_e32 v200, v102
	v_exp_f32_e32 v201, v103
	ds_read_b128 v[100:103], v195 offset:18432
	v_exp_f32_e32 v188, v104
	v_exp_f32_e32 v189, v105
	v_exp_f32_e32 v190, v106
	v_exp_f32_e32 v191, v107
	v_exp_f32_e32 v192, v96
	v_exp_f32_e32 v193, v97
	v_exp_f32_e32 v196, v98
	v_exp_f32_e32 v197, v99
	v_cvt_pk_bf16_f32 v104, v184, v185
	v_cvt_pk_bf16_f32 v105, v186, v187
	v_cvt_pk_bf16_f32 v106, v188, v189
	v_cvt_pk_bf16_f32 v107, v190, v191
	v_cvt_pk_bf16_f32 v96, v192, v193
	v_cvt_pk_bf16_f32 v97, v196, v197
	v_cvt_pk_bf16_f32 v98, v198, v199
	v_cvt_pk_bf16_f32 v99, v200, v201
	s_waitcnt lgkmcnt(1)
	s_setprio 2
	v_mfma_f32_16x16x32_bf16 v[60:63], v[108:111], v[104:107], v[60:63]
	v_exp_f32_e32 v202, v92
	v_exp_f32_e32 v203, v93
	v_exp_f32_e32 v204, v94
	v_mfma_f32_16x16x32_bf16 v[28:31], v[108:111], v[96:99], v[28:31]
	v_exp_f32_e32 v205, v95
	v_add_u32_e32 v194, v194, v181
	v_exp_f32_e32 v206, v88
	s_waitcnt lgkmcnt(0)
	v_mfma_f32_16x16x32_bf16 v[56:59], v[100:103], v[104:107], v[56:59]
	v_exp_f32_e32 v207, v89
	v_exp_f32_e32 v208, v90
	v_exp_f32_e32 v209, v91
	v_mfma_f32_16x16x32_bf16 v[24:27], v[100:103], v[96:99], v[24:27]
	ds_read_b128 v[100:103], v195 offset:20480
	ds_read_b128 v[108:111], v195 offset:22528
	ds_read_b128 v[92:95], v195 offset:28672
	v_cvt_pk_bf16_f32 v88, v202, v203
	s_waitcnt lgkmcnt(2)
	v_mfma_f32_16x16x32_bf16 v[52:55], v[100:103], v[104:107], v[52:55]
	v_cvt_pk_bf16_f32 v89, v204, v205
	v_cvt_pk_bf16_f32 v90, v206, v207
	v_cvt_pk_bf16_f32 v91, v208, v209
	v_mfma_f32_16x16x32_bf16 v[20:23], v[100:103], v[96:99], v[20:23]
	ds_read_b128 v[100:103], v195 offset:24576
	s_xor_b32 s24, s24, 1
	s_cmp_gt_i32 s25, -1
	s_waitcnt lgkmcnt(2)
	v_mfma_f32_16x16x32_bf16 v[48:51], v[108:111], v[104:107], v[48:51]
	v_mfma_f32_16x16x32_bf16 v[16:19], v[108:111], v[96:99], v[16:19]
	ds_read_b128 v[108:111], v195 offset:26624
	s_waitcnt lgkmcnt(1)
	v_mfma_f32_16x16x32_bf16 v[44:47], v[100:103], v[104:107], v[44:47]
	v_mfma_f32_16x16x32_bf16 v[12:15], v[100:103], v[96:99], v[12:15]
	ds_read_b128 v[100:103], v195 offset:30720
	s_waitcnt lgkmcnt(1)
	v_mfma_f32_16x16x32_bf16 v[40:43], v[108:111], v[104:107], v[40:43]
	v_mfma_f32_16x16x32_bf16 v[8:11], v[108:111], v[96:99], v[8:11]
	v_exp_f32_e32 v108, v80
	v_exp_f32_e32 v109, v81
	v_exp_f32_e32 v110, v82
	v_exp_f32_e32 v111, v83
	ds_read_b128 v[80:83], v194 offset:16384
	v_mfma_f32_16x16x32_bf16 v[36:39], v[92:95], v[104:107], v[36:39]
	v_mfma_f32_16x16x32_bf16 v[4:7], v[92:95], v[96:99], v[4:7]
	ds_read_b128 v[92:95], v194 offset:18432
	s_waitcnt lgkmcnt(2)
	v_mfma_f32_16x16x32_bf16 v[32:35], v[100:103], v[104:107], v[32:35]
	v_exp_f32_e32 v104, v84
	v_exp_f32_e32 v105, v85
	v_exp_f32_e32 v106, v86
	v_mfma_f32_16x16x32_bf16 v[0:3], v[100:103], v[96:99], v[0:3]
	v_exp_f32_e32 v96, v87
	v_cvt_pk_bf16_f32 v84, v108, v109
	v_cvt_pk_bf16_f32 v85, v110, v111
	v_cvt_pk_bf16_f32 v86, v104, v105
	v_cvt_pk_bf16_f32 v87, v106, v96
	s_waitcnt lgkmcnt(1)
	v_mfma_f32_16x16x32_bf16 v[60:63], v[80:83], v[88:91], v[60:63]
	v_add_f32_e32 v97, 0, v184
	v_add_f32_e32 v97, v185, v97
	v_add_f32_e32 v97, v186, v97
	v_mfma_f32_16x16x32_bf16 v[28:31], v[80:83], v[84:87], v[28:31]
	ds_read_b128 v[80:83], v194 offset:20480
	s_waitcnt lgkmcnt(1)
	v_mfma_f32_16x16x32_bf16 v[56:59], v[92:95], v[88:91], v[56:59]
	v_mfma_f32_16x16x32_bf16 v[24:27], v[92:95], v[84:87], v[24:27]
	v_add_f32_e32 v92, v187, v97
	v_add_f32_e32 v97, v188, v92
	ds_read_b128 v[92:95], v194 offset:22528
	v_add_f32_e32 v97, v189, v97
	v_add_f32_e32 v97, v190, v97
	v_add_f32_e32 v97, v191, v97
	s_waitcnt lgkmcnt(1)
	v_mfma_f32_16x16x32_bf16 v[52:55], v[80:83], v[88:91], v[52:55]
	v_mfma_f32_16x16x32_bf16 v[20:23], v[80:83], v[84:87], v[20:23]
	v_add_f32_e32 v80, v202, v97
	v_add_f32_e32 v97, v203, v80
	ds_read_b128 v[80:83], v194 offset:24576
	v_add_f32_e32 v97, v204, v97
	v_add_f32_e32 v97, v205, v97
	v_add_f32_e32 v97, v206, v97
	s_waitcnt lgkmcnt(1)
	v_mfma_f32_16x16x32_bf16 v[48:51], v[92:95], v[88:91], v[48:51]
	v_mfma_f32_16x16x32_bf16 v[16:19], v[92:95], v[84:87], v[16:19]
	v_add_f32_e32 v92, v207, v97
	v_add_f32_e32 v97, v208, v92
	ds_read_b128 v[92:95], v194 offset:26624
	v_add_f32_e32 v97, v209, v97
	v_add_f32_e32 v145, v145, v97
	v_add_f32_e32 v97, 0, v192
	s_waitcnt lgkmcnt(1)
	v_mfma_f32_16x16x32_bf16 v[44:47], v[80:83], v[88:91], v[44:47]
	v_mfma_f32_16x16x32_bf16 v[12:15], v[80:83], v[84:87], v[12:15]
	v_add_f32_e32 v80, v193, v97
	v_add_f32_e32 v97, v196, v80
	v_add_f32_e32 v97, v197, v97
	v_add_f32_e32 v97, v198, v97
	ds_read_b128 v[80:83], v194 offset:28672
	v_add_f32_e32 v97, v199, v97
	s_waitcnt lgkmcnt(1)
	v_mfma_f32_16x16x32_bf16 v[40:43], v[92:95], v[88:91], v[40:43]
	v_mfma_f32_16x16x32_bf16 v[8:11], v[92:95], v[84:87], v[8:11]
	v_add_f32_e32 v92, v200, v97
	v_add_f32_e32 v97, v201, v92
	ds_read_b128 v[92:95], v194 offset:30720
	v_add_f32_e32 v97, v108, v97
	v_add_f32_e32 v97, v109, v97
	v_add_f32_e32 v97, v110, v97
	s_waitcnt lgkmcnt(1)
	v_mfma_f32_16x16x32_bf16 v[36:39], v[80:83], v[88:91], v[36:39]
	s_waitcnt vmcnt(0)
	s_waitcnt lgkmcnt(0)
	s_barrier
	v_mfma_f32_16x16x32_bf16 v[4:7], v[80:83], v[84:87], v[4:7]
	v_add_f32_e32 v80, v111, v97
	v_add_f32_e32 v80, v104, v80
	v_add_f32_e32 v80, v105, v80
	v_mfma_f32_16x16x32_bf16 v[32:35], v[92:95], v[88:91], v[32:35]
	v_add_f32_e32 v80, v106, v80
	v_add_f32_e32 v80, v96, v80
	v_add_f32_e32 v144, v144, v80
	v_mfma_f32_16x16x32_bf16 v[0:3], v[92:95], v[84:87], v[0:3]
	s_setprio 0
	s_cbranch_scc1 .LBB0_820
	ds_bpermute_b32 v65, v163, v145
	ds_bpermute_b32 v64, v163, v144
	s_waitcnt lgkmcnt(0)
	v_pk_add_f32 v[64:65], v[144:145], v[64:65]
	ds_bpermute_b32 v67, v162, v65
	ds_bpermute_b32 v66, v162, v64
	s_waitcnt lgkmcnt(0)
	v_pk_add_f32 v[64:65], v[64:65], v[66:67]
	s_branch .LBB0_839
